# attention: per-head gate values for the compressed-branch staging and the final combine are requested together instead of one load-and-wait per head
# baseline (speedup 1.0000x reference)
.LBB0_1548:
	v_mov_b32_e32 v8, v181
	s_waitcnt lgkmcnt(0)
	s_add_u32 s40, s90, 0x15d00000
	v_and_b32_e32 v9, 15, v8
	v_or_b32_e32 v2, s97, v9
	v_readlane_b32 s4, v243, 32
	s_addc_u32 s41, s91, 0
	v_ashrrev_i32_e32 v3, 31, v2
	v_readlane_b32 s5, v243, 33
	v_mov_b64_e32 v[4:5], s[40:41]
	s_movk_i32 s12, 0x60
	v_lshl_add_u64 v[2:3], v[2:3], 0, s[4:5]
	v_mad_u64_u32 v[6:7], s[4:5], v2, s12, v[4:5]
	v_readlane_b32 s4, v243, 34
	v_mad_i32_i24 v7, v3, s12, v7
	v_lshlrev_b32_e32 v2, 10, v9
	v_and_b32_e32 v3, -16, v8
	s_lshl_b32 s34, s4, 2
	s_mov_b32 s35, s49
	v_add3_u32 v9, s96, v2, v3
	v_lshl_add_u64 v[2:3], v[6:7], 0, s[34:35]
	global_load_dword v8, v[2:3], off
	v_readlane_b32 s4, v243, 35
	s_lshl_b32 s28, s4, 2
	s_mov_b32 s29, s49
	v_lshl_add_u64 v[6:7], v[6:7], 0, s[28:29]
	global_load_dword v246, v[6:7], off
	global_load_dword v247, v[6:7], off offset:12
	global_load_dword v248, v[6:7], off offset:24
	v_readlane_b32 s4, v243, 29
	s_add_u32 s18, s90, s4
	s_addc_u32 s19, s91, 0
	s_mov_b32 s23, 0
	s_waitcnt vmcnt(0)
	v_pk_mul_f32 v[4:5], v[98:99], v[8:9] op_sel_hi:[1,0]
	v_pk_mul_f32 v[2:3], v[96:97], v[8:9] op_sel_hi:[1,0]
	ds_write_b128 v9, v[2:5]
	v_pk_mul_f32 v[4:5], v[106:107], v[8:9] op_sel_hi:[1,0]
	v_pk_mul_f32 v[2:3], v[104:105], v[8:9] op_sel_hi:[1,0]
	ds_write_b128 v9, v[2:5] offset:64
	v_pk_mul_f32 v[4:5], v[102:103], v[8:9] op_sel_hi:[1,0]
	v_pk_mul_f32 v[2:3], v[100:101], v[8:9] op_sel_hi:[1,0]
	ds_write_b128 v9, v[2:5] offset:128
	v_pk_mul_f32 v[4:5], v[94:95], v[8:9] op_sel_hi:[1,0]
	v_pk_mul_f32 v[2:3], v[92:93], v[8:9] op_sel_hi:[1,0]
	v_mov_b32_e32 v8, v246
	ds_write_b128 v9, v[2:5] offset:192
	s_nop 0
	v_pk_mul_f32 v[4:5], v[90:91], v[8:9] op_sel_hi:[1,0]
	v_pk_mul_f32 v[2:3], v[88:89], v[8:9] op_sel_hi:[1,0]
	ds_write_b128 v9, v[2:5] offset:256
	v_pk_mul_f32 v[4:5], v[86:87], v[8:9] op_sel_hi:[1,0]
	v_pk_mul_f32 v[2:3], v[84:85], v[8:9] op_sel_hi:[1,0]
	ds_write_b128 v9, v[2:5] offset:320
	v_pk_mul_f32 v[4:5], v[82:83], v[8:9] op_sel_hi:[1,0]
	v_pk_mul_f32 v[2:3], v[80:81], v[8:9] op_sel_hi:[1,0]
	ds_write_b128 v9, v[2:5] offset:384
	v_pk_mul_f32 v[4:5], v[78:79], v[8:9] op_sel_hi:[1,0]
	v_pk_mul_f32 v[2:3], v[76:77], v[8:9] op_sel_hi:[1,0]
	v_mov_b32_e32 v8, v247
	ds_write_b128 v9, v[2:5] offset:448
	v_mov_b32_e32 v6, v248
	s_nop 0
	v_pk_mul_f32 v[4:5], v[74:75], v[8:9] op_sel_hi:[1,0]
	v_pk_mul_f32 v[2:3], v[72:73], v[8:9] op_sel_hi:[1,0]
	ds_write_b128 v9, v[2:5] offset:512
	v_pk_mul_f32 v[4:5], v[70:71], v[8:9] op_sel_hi:[1,0]
	v_pk_mul_f32 v[2:3], v[68:69], v[8:9] op_sel_hi:[1,0]
	ds_write_b128 v9, v[2:5] offset:576
	v_pk_mul_f32 v[4:5], v[66:67], v[8:9] op_sel_hi:[1,0]
	v_pk_mul_f32 v[2:3], v[64:65], v[8:9] op_sel_hi:[1,0]
	ds_write_b128 v9, v[2:5] offset:640
	v_pk_mul_f32 v[4:5], v[62:63], v[8:9] op_sel_hi:[1,0]
	v_pk_mul_f32 v[2:3], v[60:61], v[8:9] op_sel_hi:[1,0]
	ds_write_b128 v9, v[2:5] offset:704
	s_nop 0
	v_pk_mul_f32 v[4:5], v[58:59], v[6:7] op_sel_hi:[1,0]
	v_pk_mul_f32 v[2:3], v[56:57], v[6:7] op_sel_hi:[1,0]
	ds_write_b128 v9, v[2:5] offset:768
	v_pk_mul_f32 v[4:5], v[54:55], v[6:7] op_sel_hi:[1,0]
	v_pk_mul_f32 v[2:3], v[52:53], v[6:7] op_sel_hi:[1,0]
	ds_write_b128 v9, v[2:5] offset:832
	v_pk_mul_f32 v[4:5], v[50:51], v[6:7] op_sel_hi:[1,0]
	v_pk_mul_f32 v[2:3], v[48:49], v[6:7] op_sel_hi:[1,0]
	ds_write_b128 v9, v[2:5] offset:896
	v_pk_mul_f32 v[4:5], v[46:47], v[6:7] op_sel_hi:[1,0]
	v_pk_mul_f32 v[2:3], v[44:45], v[6:7] op_sel_hi:[1,0]
	ds_write_b128 v9, v[2:5] offset:960
	v_mov_b32_e32 v8, v181
	s_waitcnt lgkmcnt(0)
	s_nop 0
	v_and_b32_e32 v5, 4, v8
	v_cmp_eq_u32_e64 s[12:13], 0, v5
	v_and_b32_e32 v5, 8, v8
	v_cmp_eq_u32_e64 s[14:15], 0, v5
	v_lshlrev_b32_e32 v5, 2, v8
	v_and_b32_e32 v9, 15, v8
	v_ashrrev_i32_e32 v3, 4, v8
	v_and_b32_e32 v5, 48, v5
	v_lshl_add_u32 v82, v3, 2, v5
	v_and_b32_e32 v4, 3, v8
	v_mov_b32_dpp v5, v9 row_ror:4 row_mask:0xf bank_mask:0xf bound_ctrl:1
	v_lshlrev_b32_e32 v2, 4, v8
	v_readfirstlane_b32 s4, v5
	v_lshl_add_u32 v80, v4, 9, s87
	s_cmp_eq_u32 s4, 4
	v_readlane_b32 s4, v243, 24
	v_lshlrev_b32_e32 v6, 3, v3
	v_mov_b32_e32 v3, v11
	ds_read_b32 v81, v80 offset:508
	v_or_b32_e32 v12, s4, v4
	v_lshl_add_u64 v[2:3], s[18:19], 0, v[2:3]
	s_mov_b64 s[4:5], 0x18900000
	v_lshl_add_u64 v[70:71], v[2:3], 0, s[4:5]
	s_mov_b64 s[4:5], 0x17900000
	v_lshlrev_b32_e32 v10, 7, v12
	v_lshl_add_u64 v[72:73], v[2:3], 0, s[4:5]
	v_mul_u32_u24_e32 v2, 3, v12
	v_lshl_add_u64 v[4:5], s[92:93], 0, v[10:11]
	v_ashrrev_i32_e32 v7, 31, v6
	v_lshlrev_b32_e32 v10, 2, v2
	v_lshlrev_b32_e32 v2, 8, v9
	v_and_b32_e32 v3, -16, v8
	s_cselect_b64 s[16:17], -1, 0
	v_lshl_add_u64 v[68:69], v[6:7], 1, v[4:5]
	v_lshl_add_u64 v[74:75], s[40:41], 0, v[10:11]
	v_cmp_gt_u32_e64 s[18:19], 4, v9
	v_add3_u32 v10, s96, v2, v3
	v_not_b32_e32 v83, v82
	s_add_i32 s25, s96, 0x4000
	s_branch .LBB0_1550

.LBB0_1755:
	v_mov_b32_e32 v10, v181
	v_readlane_b32 s4, v243, 32
	v_and_b32_e32 v76, 15, v10
	v_or_b32_e32 v12, s97, v76
	v_ashrrev_i32_e32 v13, 31, v12
	v_readlane_b32 s5, v243, 33
	v_mov_b64_e32 v[70:71], s[40:41]
	s_movk_i32 s2, 0x60
	v_lshl_add_u64 v[12:13], v[12:13], 0, s[4:5]
	v_ashrrev_i32_e32 v10, 2, v10
	v_mad_u64_u32 v[70:71], s[4:5], v12, s2, v[70:71]
	v_lshlrev_b32_e32 v77, 10, v76
	v_and_b32_e32 v76, -4, v10
	v_mad_i32_i24 v71, v13, s2, v71
	v_lshlrev_b32_e32 v10, 2, v76
	v_lshlrev_b64 v[12:13], 11, v[12:13]
	v_add3_u32 v10, s96, v77, v10
	v_lshl_add_u64 v[12:13], s[90:91], 0, v[12:13]
	v_ashrrev_i32_e32 v77, 31, v76
	s_mov_b32 s35, s49
	v_lshl_add_u64 v[12:13], v[76:77], 1, v[12:13]
	v_lshl_add_u64 v[76:77], v[70:71], 0, s[34:35]
	global_load_dword v76, v[76:77], off offset:8
	s_mov_b32 s98, s28
	s_mov_b32 s99, s49
	v_lshl_add_u64 v[244:245], v[70:71], 0, s[98:99]
	global_load_dword v246, v[244:245], off offset:8
	global_load_dword v247, v[244:245], off offset:20
	global_load_dword v248, v[244:245], off offset:32
	s_mov_b64 s[4:5], 0x5800000
	v_lshl_add_u64 v[12:13], v[12:13], 0, s[4:5]
	s_mov_b32 s27, s49
	v_lshl_add_u64 v[82:83], v[12:13], 0, s[26:27]
	s_mov_b32 s29, s49
	s_mov_b32 s25, s49
	s_mov_b32 s23, s49
	s_mov_b32 s21, s49
	v_readfirstlane_b32 s2, v180
	s_ashr_i32 s2, s2, 6
	s_mov_b64 s[12:13], 0
	s_waitcnt vmcnt(0)
	v_div_scale_f32 v77, s[4:5], v75, v75, v76
	v_rcp_f32_e32 v78, v77
	s_nop 0
	v_fma_f32 v79, -v77, v78, 1.0
	v_fmac_f32_e32 v78, v79, v78
	v_div_scale_f32 v79, vcc, v76, v75, v76
	v_mul_f32_e32 v80, v79, v78
	v_fma_f32 v81, -v77, v80, v79
	v_fmac_f32_e32 v80, v81, v78
	v_fma_f32 v77, -v77, v80, v79
	v_div_fmas_f32 v77, v77, v78, v80
	v_div_fixup_f32 v80, v77, v75, v76
	ds_read_b128 v[76:79], v10
	s_waitcnt lgkmcnt(0)
	v_pk_fma_f32 v[66:67], v[66:67], v[80:81], v[76:77] op_sel_hi:[1,0,1]
	v_pk_fma_f32 v[68:69], v[68:69], v[80:81], v[78:79] op_sel_hi:[1,0,1]
	v_cvt_pk_bf16_f32 v66, v66, v67
	s_nop 0
	v_cvt_pk_bf16_f32 v67, v68, v69
	global_store_dwordx2 v[82:83], v[66:67], off
	ds_read_b128 v[66:69], v10 offset:64
	s_waitcnt lgkmcnt(0)
	v_pk_fma_f32 v[62:63], v[62:63], v[80:81], v[66:67] op_sel_hi:[1,0,1]
	v_pk_fma_f32 v[64:65], v[64:65], v[80:81], v[68:69] op_sel_hi:[1,0,1]
	v_cvt_pk_bf16_f32 v62, v62, v63
	s_nop 0
	v_cvt_pk_bf16_f32 v63, v64, v65
	global_store_dwordx2 v[82:83], v[62:63], off offset:32
	ds_read_b128 v[62:65], v10 offset:128
	s_waitcnt lgkmcnt(0)
	v_pk_fma_f32 v[58:59], v[58:59], v[80:81], v[62:63] op_sel_hi:[1,0,1]
	v_pk_fma_f32 v[60:61], v[60:61], v[80:81], v[64:65] op_sel_hi:[1,0,1]
	v_cvt_pk_bf16_f32 v58, v58, v59
	v_lshl_add_u64 v[62:63], v[12:13], 0, s[24:25]
	v_cvt_pk_bf16_f32 v59, v60, v61
	global_store_dwordx2 v[82:83], v[58:59], off offset:64
	ds_read_b128 v[58:61], v10 offset:192
	s_waitcnt lgkmcnt(0)
	v_pk_fma_f32 v[54:55], v[54:55], v[80:81], v[58:59] op_sel_hi:[1,0,1]
	v_pk_fma_f32 v[56:57], v[56:57], v[80:81], v[60:61] op_sel_hi:[1,0,1]
	v_cvt_pk_bf16_f32 v54, v54, v55
	s_nop 0
	v_cvt_pk_bf16_f32 v55, v56, v57
	global_store_dwordx2 v[82:83], v[54:55], off offset:96
	v_lshl_add_u64 v[54:55], v[70:71], 0, s[28:29]
	v_mov_b32_e32 v56, v246
	s_mul_i32 s29, s2, 0x4500
	s_add_i32 s46, s29, 0
	s_nop 0
	v_div_scale_f32 v57, s[4:5], v74, v74, v56
	v_rcp_f32_e32 v58, v57
	s_nop 0
	v_fma_f32 v59, -v57, v58, 1.0
	v_fmac_f32_e32 v58, v59, v58
	v_div_scale_f32 v59, vcc, v56, v74, v56
	v_mul_f32_e32 v60, v59, v58
	v_fma_f32 v61, -v57, v60, v59
	v_fmac_f32_e32 v60, v61, v58
	v_fma_f32 v57, -v57, v60, v59
	v_div_fmas_f32 v57, v57, v58, v60
	v_div_fixup_f32 v60, v57, v74, v56
	ds_read_b128 v[56:59], v10 offset:256
	s_waitcnt lgkmcnt(0)
	v_pk_fma_f32 v[50:51], v[50:51], v[60:61], v[56:57] op_sel_hi:[1,0,1]
	v_pk_fma_f32 v[52:53], v[52:53], v[60:61], v[58:59] op_sel_hi:[1,0,1]
	v_cvt_pk_bf16_f32 v50, v50, v51
	s_nop 0
	v_cvt_pk_bf16_f32 v51, v52, v53
	global_store_dwordx2 v[62:63], v[50:51], off
	ds_read_b128 v[50:53], v10 offset:320
	s_waitcnt lgkmcnt(0)
	v_pk_fma_f32 v[46:47], v[46:47], v[60:61], v[50:51] op_sel_hi:[1,0,1]
	v_pk_fma_f32 v[48:49], v[48:49], v[60:61], v[52:53] op_sel_hi:[1,0,1]
	v_cvt_pk_bf16_f32 v46, v46, v47
	s_nop 0
	v_cvt_pk_bf16_f32 v47, v48, v49
	global_store_dwordx2 v[62:63], v[46:47], off offset:32
	ds_read_b128 v[46:49], v10 offset:384
	s_waitcnt lgkmcnt(0)
	v_pk_fma_f32 v[42:43], v[42:43], v[60:61], v[46:47] op_sel_hi:[1,0,1]
	v_pk_fma_f32 v[44:45], v[44:45], v[60:61], v[48:49] op_sel_hi:[1,0,1]
	v_cvt_pk_bf16_f32 v42, v42, v43
	s_nop 0
	v_cvt_pk_bf16_f32 v43, v44, v45
	global_store_dwordx2 v[62:63], v[42:43], off offset:64
	ds_read_b128 v[42:45], v10 offset:448
	s_waitcnt lgkmcnt(0)
	v_pk_fma_f32 v[38:39], v[38:39], v[60:61], v[42:43] op_sel_hi:[1,0,1]
	v_pk_fma_f32 v[40:41], v[40:41], v[60:61], v[44:45] op_sel_hi:[1,0,1]
	v_cvt_pk_bf16_f32 v38, v38, v39
	v_lshl_add_u64 v[44:45], v[12:13], 0, s[22:23]
	v_cvt_pk_bf16_f32 v39, v40, v41
	global_store_dwordx2 v[62:63], v[38:39], off offset:96
	v_mov_b32_e32 v38, v247
	s_nop 0
	v_div_scale_f32 v39, s[4:5], v73, v73, v38
	v_rcp_f32_e32 v40, v39
	s_nop 0
	v_fma_f32 v41, -v39, v40, 1.0
	v_fmac_f32_e32 v40, v41, v40
	v_div_scale_f32 v41, vcc, v38, v73, v38
	v_mul_f32_e32 v42, v41, v40
	v_fma_f32 v43, -v39, v42, v41
	v_fmac_f32_e32 v42, v43, v40
	v_fma_f32 v39, -v39, v42, v41
	v_div_fmas_f32 v39, v39, v40, v42
	v_div_fixup_f32 v42, v39, v73, v38
	ds_read_b128 v[38:41], v10 offset:512
	s_waitcnt lgkmcnt(0)
	v_pk_fma_f32 v[34:35], v[34:35], v[42:43], v[38:39] op_sel_hi:[1,0,1]
	v_pk_fma_f32 v[36:37], v[36:37], v[42:43], v[40:41] op_sel_hi:[1,0,1]
	v_cvt_pk_bf16_f32 v34, v34, v35
	s_nop 0
	v_cvt_pk_bf16_f32 v35, v36, v37
	global_store_dwordx2 v[44:45], v[34:35], off
	ds_read_b128 v[34:37], v10 offset:576
	s_waitcnt lgkmcnt(0)
	v_pk_fma_f32 v[30:31], v[30:31], v[42:43], v[34:35] op_sel_hi:[1,0,1]
	v_pk_fma_f32 v[32:33], v[32:33], v[42:43], v[36:37] op_sel_hi:[1,0,1]
	v_cvt_pk_bf16_f32 v30, v30, v31
	s_nop 0
	v_cvt_pk_bf16_f32 v31, v32, v33
	global_store_dwordx2 v[44:45], v[30:31], off offset:32
	ds_read_b128 v[30:33], v10 offset:640
	s_waitcnt lgkmcnt(0)
	v_pk_fma_f32 v[26:27], v[26:27], v[42:43], v[30:31] op_sel_hi:[1,0,1]
	v_pk_fma_f32 v[28:29], v[28:29], v[42:43], v[32:33] op_sel_hi:[1,0,1]
	v_cvt_pk_bf16_f32 v26, v26, v27
	s_nop 0
	v_cvt_pk_bf16_f32 v27, v28, v29
	global_store_dwordx2 v[44:45], v[26:27], off offset:64
	ds_read_b128 v[26:29], v10 offset:704
	s_waitcnt lgkmcnt(0)
	v_pk_fma_f32 v[22:23], v[22:23], v[42:43], v[26:27] op_sel_hi:[1,0,1]
	v_pk_fma_f32 v[24:25], v[24:25], v[42:43], v[28:29] op_sel_hi:[1,0,1]
	v_cvt_pk_bf16_f32 v22, v22, v23
	v_lshl_add_u64 v[28:29], v[12:13], 0, s[20:21]
	v_cvt_pk_bf16_f32 v23, v24, v25
	global_store_dwordx2 v[44:45], v[22:23], off offset:96
	v_mov_b32_e32 v22, v248
	s_nop 0
	v_div_scale_f32 v23, s[4:5], v72, v72, v22
	v_rcp_f32_e32 v24, v23
	s_mov_b64 s[4:5], s[0:1]
	v_fma_f32 v25, -v23, v24, 1.0
	v_fmac_f32_e32 v24, v25, v24
	v_div_scale_f32 v25, vcc, v22, v72, v22
	v_mul_f32_e32 v26, v25, v24
	v_fma_f32 v27, -v23, v26, v25
	v_fmac_f32_e32 v26, v27, v24
	v_fma_f32 v23, -v23, v26, v25
	v_div_fmas_f32 v23, v23, v24, v26
	v_div_fixup_f32 v26, v23, v72, v22
	ds_read_b128 v[22:25], v10 offset:768
	s_waitcnt lgkmcnt(0)
	v_pk_fma_f32 v[18:19], v[18:19], v[26:27], v[22:23] op_sel_hi:[1,0,1]
	v_pk_fma_f32 v[12:13], v[20:21], v[26:27], v[24:25] op_sel_hi:[1,0,1]
	v_cvt_pk_bf16_f32 v18, v18, v19
	s_nop 0
	v_cvt_pk_bf16_f32 v19, v12, v13
	global_store_dwordx2 v[28:29], v[18:19], off
	ds_read_b128 v[18:21], v10 offset:832
	s_waitcnt lgkmcnt(0)
	v_pk_fma_f32 v[14:15], v[14:15], v[26:27], v[18:19] op_sel_hi:[1,0,1]
	v_pk_fma_f32 v[12:13], v[16:17], v[26:27], v[20:21] op_sel_hi:[1,0,1]
	v_cvt_pk_bf16_f32 v14, v14, v15
	s_nop 0
	v_cvt_pk_bf16_f32 v15, v12, v13
	global_store_dwordx2 v[28:29], v[14:15], off offset:32
	ds_read_b128 v[12:15], v10 offset:896
	s_waitcnt lgkmcnt(0)
	v_pk_fma_f32 v[6:7], v[6:7], v[26:27], v[12:13] op_sel_hi:[1,0,1]
	v_pk_fma_f32 v[8:9], v[8:9], v[26:27], v[14:15] op_sel_hi:[1,0,1]
	v_cvt_pk_bf16_f32 v6, v6, v7
	s_nop 0
	v_cvt_pk_bf16_f32 v7, v8, v9
	global_store_dwordx2 v[28:29], v[6:7], off offset:64
	ds_read_b128 v[6:9], v10 offset:960
	s_waitcnt lgkmcnt(0)
	v_pk_fma_f32 v[2:3], v[2:3], v[26:27], v[6:7] op_sel_hi:[1,0,1]
	v_pk_fma_f32 v[4:5], v[4:5], v[26:27], v[8:9] op_sel_hi:[1,0,1]
	v_cvt_pk_bf16_f32 v2, v2, v3
	s_nop 0
	v_cvt_pk_bf16_f32 v3, v4, v5
	global_store_dwordx2 v[28:29], v[2:3], off offset:96
	s_waitcnt lgkmcnt(0)
	s_load_dwordx2 s[16:17], s[4:5], 0xd8
	v_add_u32_e32 v2, s46, v222

.LBB0_2048:
	v_mov_b32_e32 v8, v181
	s_waitcnt lgkmcnt(0)
	s_add_u32 s14, s16, 0x15d00000
	v_and_b32_e32 v9, 15, v8
	v_or_b32_e32 v2, s47, v9
	v_readlane_b32 s4, v243, 32
	s_addc_u32 s15, s17, 0
	v_ashrrev_i32_e32 v3, 31, v2
	v_readlane_b32 s5, v243, 33
	v_mov_b64_e32 v[4:5], s[14:15]
	s_movk_i32 s6, 0x60
	v_lshl_add_u64 v[2:3], v[2:3], 0, s[4:5]
	v_mad_u64_u32 v[6:7], s[4:5], v2, s6, v[4:5]
	v_mad_i32_i24 v7, v3, s6, v7
	v_lshlrev_b32_e32 v2, 10, v9
	v_and_b32_e32 v3, -16, v8
	s_mov_b32 s35, s49
	v_add3_u32 v9, s46, v2, v3
	v_lshl_add_u64 v[2:3], v[6:7], 0, s[34:35]
	global_load_dword v8, v[2:3], off
	s_mov_b32 s29, s49
	v_lshl_add_u64 v[6:7], v[6:7], 0, s[28:29]
	global_load_dword v246, v[6:7], off
	global_load_dword v247, v[6:7], off offset:12
	global_load_dword v248, v[6:7], off offset:24
	v_readlane_b32 s4, v243, 29
	s_add_u32 s12, s16, s4
	s_addc_u32 s13, s17, 0
	s_mov_b32 s23, 0
	s_waitcnt vmcnt(0)
	v_pk_mul_f32 v[4:5], v[98:99], v[8:9] op_sel_hi:[1,0]
	v_pk_mul_f32 v[2:3], v[96:97], v[8:9] op_sel_hi:[1,0]
	ds_write_b128 v9, v[2:5]
	v_pk_mul_f32 v[4:5], v[106:107], v[8:9] op_sel_hi:[1,0]
	v_pk_mul_f32 v[2:3], v[104:105], v[8:9] op_sel_hi:[1,0]
	ds_write_b128 v9, v[2:5] offset:64
	v_pk_mul_f32 v[4:5], v[102:103], v[8:9] op_sel_hi:[1,0]
	v_pk_mul_f32 v[2:3], v[100:101], v[8:9] op_sel_hi:[1,0]
	ds_write_b128 v9, v[2:5] offset:128
	v_pk_mul_f32 v[4:5], v[94:95], v[8:9] op_sel_hi:[1,0]
	v_pk_mul_f32 v[2:3], v[92:93], v[8:9] op_sel_hi:[1,0]
	v_mov_b32_e32 v8, v246
	ds_write_b128 v9, v[2:5] offset:192
	s_nop 0
	v_pk_mul_f32 v[4:5], v[90:91], v[8:9] op_sel_hi:[1,0]
	v_pk_mul_f32 v[2:3], v[88:89], v[8:9] op_sel_hi:[1,0]
	ds_write_b128 v9, v[2:5] offset:256
	v_pk_mul_f32 v[4:5], v[86:87], v[8:9] op_sel_hi:[1,0]
	v_pk_mul_f32 v[2:3], v[84:85], v[8:9] op_sel_hi:[1,0]
	ds_write_b128 v9, v[2:5] offset:320
	v_pk_mul_f32 v[4:5], v[82:83], v[8:9] op_sel_hi:[1,0]
	v_pk_mul_f32 v[2:3], v[80:81], v[8:9] op_sel_hi:[1,0]
	ds_write_b128 v9, v[2:5] offset:384
	v_pk_mul_f32 v[4:5], v[78:79], v[8:9] op_sel_hi:[1,0]
	v_pk_mul_f32 v[2:3], v[76:77], v[8:9] op_sel_hi:[1,0]
	v_mov_b32_e32 v8, v247
	ds_write_b128 v9, v[2:5] offset:448
	v_mov_b32_e32 v6, v248
	s_nop 0
	v_pk_mul_f32 v[4:5], v[74:75], v[8:9] op_sel_hi:[1,0]
	v_pk_mul_f32 v[2:3], v[72:73], v[8:9] op_sel_hi:[1,0]
	ds_write_b128 v9, v[2:5] offset:512
	v_pk_mul_f32 v[4:5], v[70:71], v[8:9] op_sel_hi:[1,0]
	v_pk_mul_f32 v[2:3], v[68:69], v[8:9] op_sel_hi:[1,0]
	ds_write_b128 v9, v[2:5] offset:576
	v_pk_mul_f32 v[4:5], v[66:67], v[8:9] op_sel_hi:[1,0]
	v_pk_mul_f32 v[2:3], v[64:65], v[8:9] op_sel_hi:[1,0]
	ds_write_b128 v9, v[2:5] offset:640
	v_pk_mul_f32 v[4:5], v[62:63], v[8:9] op_sel_hi:[1,0]
	v_pk_mul_f32 v[2:3], v[60:61], v[8:9] op_sel_hi:[1,0]
	ds_write_b128 v9, v[2:5] offset:704
	s_nop 0
	v_pk_mul_f32 v[4:5], v[58:59], v[6:7] op_sel_hi:[1,0]
	v_pk_mul_f32 v[2:3], v[56:57], v[6:7] op_sel_hi:[1,0]
	ds_write_b128 v9, v[2:5] offset:768
	v_pk_mul_f32 v[4:5], v[54:55], v[6:7] op_sel_hi:[1,0]
	v_pk_mul_f32 v[2:3], v[52:53], v[6:7] op_sel_hi:[1,0]
	ds_write_b128 v9, v[2:5] offset:832
	v_pk_mul_f32 v[4:5], v[50:51], v[6:7] op_sel_hi:[1,0]
	v_pk_mul_f32 v[2:3], v[48:49], v[6:7] op_sel_hi:[1,0]
	ds_write_b128 v9, v[2:5] offset:896
	v_pk_mul_f32 v[4:5], v[46:47], v[6:7] op_sel_hi:[1,0]
	v_pk_mul_f32 v[2:3], v[44:45], v[6:7] op_sel_hi:[1,0]
	ds_write_b128 v9, v[2:5] offset:960
	v_mov_b32_e32 v8, v181
	s_waitcnt lgkmcnt(0)
	s_nop 0
	v_and_b32_e32 v5, 4, v8
	v_cmp_eq_u32_e64 s[6:7], 0, v5
	v_and_b32_e32 v5, 8, v8
	v_cmp_eq_u32_e64 s[8:9], 0, v5
	v_lshlrev_b32_e32 v5, 2, v8
	v_and_b32_e32 v9, 15, v8
	v_ashrrev_i32_e32 v3, 4, v8
	v_and_b32_e32 v5, 48, v5
	v_lshl_add_u32 v82, v3, 2, v5
	v_and_b32_e32 v4, 3, v8
	v_mov_b32_dpp v5, v9 row_ror:4 row_mask:0xf bank_mask:0xf bound_ctrl:1
	v_lshlrev_b32_e32 v2, 4, v8
	v_readfirstlane_b32 s4, v5
	v_lshl_add_u32 v80, v4, 9, s87
	s_cmp_eq_u32 s4, 4
	v_readlane_b32 s4, v243, 24
	v_lshlrev_b32_e32 v6, 3, v3
	v_mov_b32_e32 v3, v11
	ds_read_b32 v81, v80 offset:508
	v_or_b32_e32 v12, s4, v4
	v_lshl_add_u64 v[2:3], s[12:13], 0, v[2:3]
	s_mov_b64 s[4:5], 0x18900000
	v_lshl_add_u64 v[70:71], v[2:3], 0, s[4:5]
	s_mov_b64 s[4:5], 0x17900000
	v_lshlrev_b32_e32 v10, 7, v12
	v_lshl_add_u64 v[72:73], v[2:3], 0, s[4:5]
	v_mul_u32_u24_e32 v2, 3, v12
	v_lshl_add_u64 v[4:5], s[18:19], 0, v[10:11]
	v_ashrrev_i32_e32 v7, 31, v6
	v_lshlrev_b32_e32 v10, 2, v2
	v_lshlrev_b32_e32 v2, 8, v9
	v_and_b32_e32 v3, -16, v8
	s_cselect_b64 s[10:11], -1, 0
	v_lshl_add_u64 v[68:69], v[6:7], 1, v[4:5]
	v_lshl_add_u64 v[74:75], s[14:15], 0, v[10:11]
	v_cmp_gt_u32_e64 s[12:13], 4, v9
	v_add3_u32 v10, s46, v2, v3
	v_not_b32_e32 v83, v82
	s_add_i32 s25, s46, 0x4000
	s_branch .LBB0_2050

.LBB0_2255:
	v_readlane_b32 s4, v243, 32
	v_and_b32_e32 v10, 15, v181
	v_or_b32_e32 v12, s47, v10
	v_ashrrev_i32_e32 v13, 31, v12
	v_readlane_b32 s5, v243, 33
	v_mov_b64_e32 v[70:71], s[14:15]
	s_movk_i32 s2, 0x60
	v_lshl_add_u64 v[12:13], v[12:13], 0, s[4:5]
	v_ashrrev_i32_e32 v76, 2, v181
	v_mad_u64_u32 v[70:71], s[4:5], v12, s2, v[70:71]
	v_and_b32_e32 v76, -4, v76
	v_mad_i32_i24 v71, v13, s2, v71
	v_lshlrev_b32_e32 v10, 10, v10
	v_lshlrev_b32_e32 v77, 2, v76
	v_lshlrev_b64 v[12:13], 11, v[12:13]
	v_add3_u32 v10, s46, v10, v77
	v_lshl_add_u64 v[12:13], s[16:17], 0, v[12:13]
	v_ashrrev_i32_e32 v77, 31, v76
	s_mov_b32 s35, s49
	v_lshl_add_u64 v[12:13], v[76:77], 1, v[12:13]
	v_lshl_add_u64 v[76:77], v[70:71], 0, s[34:35]
	global_load_dword v76, v[76:77], off offset:8
	s_mov_b32 s98, s28
	s_mov_b32 s99, s49
	v_lshl_add_u64 v[244:245], v[70:71], 0, s[98:99]
	global_load_dword v246, v[244:245], off offset:8
	global_load_dword v247, v[244:245], off offset:20
	global_load_dword v248, v[244:245], off offset:32
	s_mov_b64 s[4:5], 0x5800000
	v_lshl_add_u64 v[12:13], v[12:13], 0, s[4:5]
	s_mov_b32 s27, s49
	v_lshl_add_u64 v[82:83], v[12:13], 0, s[26:27]
	s_mov_b32 s29, s49
	s_mov_b32 s25, s49
	s_mov_b32 s23, s49
	s_mov_b32 s21, s49
	s_movk_i32 s83, 0x60
	s_waitcnt vmcnt(0)
	v_div_scale_f32 v77, s[4:5], v75, v75, v76
	v_rcp_f32_e32 v78, v77
	s_nop 0
	v_fma_f32 v79, -v77, v78, 1.0
	v_fmac_f32_e32 v78, v79, v78
	v_div_scale_f32 v79, vcc, v76, v75, v76
	v_mul_f32_e32 v80, v79, v78
	v_fma_f32 v81, -v77, v80, v79
	v_fmac_f32_e32 v80, v81, v78
	v_fma_f32 v77, -v77, v80, v79
	v_div_fmas_f32 v77, v77, v78, v80
	v_div_fixup_f32 v80, v77, v75, v76
	ds_read_b128 v[76:79], v10
	s_waitcnt lgkmcnt(0)
	v_pk_fma_f32 v[66:67], v[66:67], v[80:81], v[76:77] op_sel_hi:[1,0,1]
	v_pk_fma_f32 v[68:69], v[68:69], v[80:81], v[78:79] op_sel_hi:[1,0,1]
	v_cvt_pk_bf16_f32 v66, v66, v67
	s_nop 0
	v_cvt_pk_bf16_f32 v67, v68, v69
	global_store_dwordx2 v[82:83], v[66:67], off
	ds_read_b128 v[66:69], v10 offset:64
	s_waitcnt lgkmcnt(0)
	v_pk_fma_f32 v[62:63], v[62:63], v[80:81], v[66:67] op_sel_hi:[1,0,1]
	v_pk_fma_f32 v[64:65], v[64:65], v[80:81], v[68:69] op_sel_hi:[1,0,1]
	v_cvt_pk_bf16_f32 v62, v62, v63
	s_nop 0
	v_cvt_pk_bf16_f32 v63, v64, v65
	global_store_dwordx2 v[82:83], v[62:63], off offset:32
	ds_read_b128 v[62:65], v10 offset:128
	s_waitcnt lgkmcnt(0)
	v_pk_fma_f32 v[58:59], v[58:59], v[80:81], v[62:63] op_sel_hi:[1,0,1]
	v_pk_fma_f32 v[60:61], v[60:61], v[80:81], v[64:65] op_sel_hi:[1,0,1]
	v_cvt_pk_bf16_f32 v58, v58, v59
	v_lshl_add_u64 v[62:63], v[12:13], 0, s[24:25]
	v_cvt_pk_bf16_f32 v59, v60, v61
	global_store_dwordx2 v[82:83], v[58:59], off offset:64
	ds_read_b128 v[58:61], v10 offset:192
	s_waitcnt lgkmcnt(0)
	v_pk_fma_f32 v[54:55], v[54:55], v[80:81], v[58:59] op_sel_hi:[1,0,1]
	v_pk_fma_f32 v[56:57], v[56:57], v[80:81], v[60:61] op_sel_hi:[1,0,1]
	v_cvt_pk_bf16_f32 v54, v54, v55
	s_nop 0
	v_cvt_pk_bf16_f32 v55, v56, v57
	global_store_dwordx2 v[82:83], v[54:55], off offset:96
	v_lshl_add_u64 v[54:55], v[70:71], 0, s[28:29]
	v_mov_b32_e32 v56, v246
	s_nop 0
	v_div_scale_f32 v57, s[4:5], v74, v74, v56
	v_rcp_f32_e32 v58, v57
	s_nop 0
	v_fma_f32 v59, -v57, v58, 1.0
	v_fmac_f32_e32 v58, v59, v58
	v_div_scale_f32 v59, vcc, v56, v74, v56
	v_mul_f32_e32 v60, v59, v58
	v_fma_f32 v61, -v57, v60, v59
	v_fmac_f32_e32 v60, v61, v58
	v_fma_f32 v57, -v57, v60, v59
	v_div_fmas_f32 v57, v57, v58, v60
	v_div_fixup_f32 v60, v57, v74, v56
	ds_read_b128 v[56:59], v10 offset:256
	s_waitcnt lgkmcnt(0)
	v_pk_fma_f32 v[50:51], v[50:51], v[60:61], v[56:57] op_sel_hi:[1,0,1]
	v_pk_fma_f32 v[52:53], v[52:53], v[60:61], v[58:59] op_sel_hi:[1,0,1]
	v_cvt_pk_bf16_f32 v50, v50, v51
	s_nop 0
	v_cvt_pk_bf16_f32 v51, v52, v53
	global_store_dwordx2 v[62:63], v[50:51], off
	ds_read_b128 v[50:53], v10 offset:320
	s_waitcnt lgkmcnt(0)
	v_pk_fma_f32 v[46:47], v[46:47], v[60:61], v[50:51] op_sel_hi:[1,0,1]
	v_pk_fma_f32 v[48:49], v[48:49], v[60:61], v[52:53] op_sel_hi:[1,0,1]
	v_cvt_pk_bf16_f32 v46, v46, v47
	s_nop 0
	v_cvt_pk_bf16_f32 v47, v48, v49
	global_store_dwordx2 v[62:63], v[46:47], off offset:32
	ds_read_b128 v[46:49], v10 offset:384
	s_waitcnt lgkmcnt(0)
	v_pk_fma_f32 v[42:43], v[42:43], v[60:61], v[46:47] op_sel_hi:[1,0,1]
	v_pk_fma_f32 v[44:45], v[44:45], v[60:61], v[48:49] op_sel_hi:[1,0,1]
	v_cvt_pk_bf16_f32 v42, v42, v43
	s_nop 0
	v_cvt_pk_bf16_f32 v43, v44, v45
	global_store_dwordx2 v[62:63], v[42:43], off offset:64
	ds_read_b128 v[42:45], v10 offset:448
	s_waitcnt lgkmcnt(0)
	v_pk_fma_f32 v[38:39], v[38:39], v[60:61], v[42:43] op_sel_hi:[1,0,1]
	v_pk_fma_f32 v[40:41], v[40:41], v[60:61], v[44:45] op_sel_hi:[1,0,1]
	v_cvt_pk_bf16_f32 v38, v38, v39
	v_lshl_add_u64 v[44:45], v[12:13], 0, s[22:23]
	v_cvt_pk_bf16_f32 v39, v40, v41
	global_store_dwordx2 v[62:63], v[38:39], off offset:96
	v_mov_b32_e32 v38, v247
	s_nop 0
	v_div_scale_f32 v39, s[4:5], v73, v73, v38
	v_rcp_f32_e32 v40, v39
	s_nop 0
	v_fma_f32 v41, -v39, v40, 1.0
	v_fmac_f32_e32 v40, v41, v40
	v_div_scale_f32 v41, vcc, v38, v73, v38
	v_mul_f32_e32 v42, v41, v40
	v_fma_f32 v43, -v39, v42, v41
	v_fmac_f32_e32 v42, v43, v40
	v_fma_f32 v39, -v39, v42, v41
	v_div_fmas_f32 v39, v39, v40, v42
	v_div_fixup_f32 v42, v39, v73, v38
	ds_read_b128 v[38:41], v10 offset:512
	s_waitcnt lgkmcnt(0)
	v_pk_fma_f32 v[34:35], v[34:35], v[42:43], v[38:39] op_sel_hi:[1,0,1]
	v_pk_fma_f32 v[36:37], v[36:37], v[42:43], v[40:41] op_sel_hi:[1,0,1]
	v_cvt_pk_bf16_f32 v34, v34, v35
	s_nop 0
	v_cvt_pk_bf16_f32 v35, v36, v37
	global_store_dwordx2 v[44:45], v[34:35], off
	ds_read_b128 v[34:37], v10 offset:576
	s_waitcnt lgkmcnt(0)
	v_pk_fma_f32 v[30:31], v[30:31], v[42:43], v[34:35] op_sel_hi:[1,0,1]
	v_pk_fma_f32 v[32:33], v[32:33], v[42:43], v[36:37] op_sel_hi:[1,0,1]
	v_cvt_pk_bf16_f32 v30, v30, v31
	s_nop 0
	v_cvt_pk_bf16_f32 v31, v32, v33
	global_store_dwordx2 v[44:45], v[30:31], off offset:32
	ds_read_b128 v[30:33], v10 offset:640
	s_waitcnt lgkmcnt(0)
	v_pk_fma_f32 v[26:27], v[26:27], v[42:43], v[30:31] op_sel_hi:[1,0,1]
	v_pk_fma_f32 v[28:29], v[28:29], v[42:43], v[32:33] op_sel_hi:[1,0,1]
	v_cvt_pk_bf16_f32 v26, v26, v27
	s_nop 0
	v_cvt_pk_bf16_f32 v27, v28, v29
	global_store_dwordx2 v[44:45], v[26:27], off offset:64
	ds_read_b128 v[26:29], v10 offset:704
	s_waitcnt lgkmcnt(0)
	v_pk_fma_f32 v[22:23], v[22:23], v[42:43], v[26:27] op_sel_hi:[1,0,1]
	v_pk_fma_f32 v[24:25], v[24:25], v[42:43], v[28:29] op_sel_hi:[1,0,1]
	v_cvt_pk_bf16_f32 v22, v22, v23
	v_lshl_add_u64 v[28:29], v[12:13], 0, s[20:21]
	v_cvt_pk_bf16_f32 v23, v24, v25
	global_store_dwordx2 v[44:45], v[22:23], off offset:96
	v_mov_b32_e32 v22, v248
	s_nop 0
	v_div_scale_f32 v23, s[4:5], v72, v72, v22
	v_rcp_f32_e32 v24, v23
	s_nop 0
	v_fma_f32 v25, -v23, v24, 1.0
	v_fmac_f32_e32 v24, v25, v24
	v_div_scale_f32 v25, vcc, v22, v72, v22
	v_mul_f32_e32 v26, v25, v24
	v_fma_f32 v27, -v23, v26, v25
	v_fmac_f32_e32 v26, v27, v24
	v_fma_f32 v23, -v23, v26, v25
	v_div_fmas_f32 v23, v23, v24, v26
	v_div_fixup_f32 v26, v23, v72, v22
	ds_read_b128 v[22:25], v10 offset:768
	s_waitcnt lgkmcnt(0)
	v_pk_fma_f32 v[18:19], v[18:19], v[26:27], v[22:23] op_sel_hi:[1,0,1]
	v_pk_fma_f32 v[12:13], v[20:21], v[26:27], v[24:25] op_sel_hi:[1,0,1]
	v_cvt_pk_bf16_f32 v18, v18, v19
	s_nop 0
	v_cvt_pk_bf16_f32 v19, v12, v13
	global_store_dwordx2 v[28:29], v[18:19], off
	ds_read_b128 v[18:21], v10 offset:832
	s_waitcnt lgkmcnt(0)
	v_pk_fma_f32 v[14:15], v[14:15], v[26:27], v[18:19] op_sel_hi:[1,0,1]
	v_pk_fma_f32 v[12:13], v[16:17], v[26:27], v[20:21] op_sel_hi:[1,0,1]
	v_cvt_pk_bf16_f32 v14, v14, v15
	s_nop 0
	v_cvt_pk_bf16_f32 v15, v12, v13
	global_store_dwordx2 v[28:29], v[14:15], off offset:32
	ds_read_b128 v[12:15], v10 offset:896
	s_waitcnt lgkmcnt(0)
	v_pk_fma_f32 v[6:7], v[6:7], v[26:27], v[12:13] op_sel_hi:[1,0,1]
	v_pk_fma_f32 v[8:9], v[8:9], v[26:27], v[14:15] op_sel_hi:[1,0,1]
	v_cvt_pk_bf16_f32 v6, v6, v7
	s_nop 0
	v_cvt_pk_bf16_f32 v7, v8, v9
	global_store_dwordx2 v[28:29], v[6:7], off offset:64
	ds_read_b128 v[6:9], v10 offset:960
	s_waitcnt lgkmcnt(0)
	v_pk_fma_f32 v[2:3], v[2:3], v[26:27], v[6:7] op_sel_hi:[1,0,1]
	v_pk_fma_f32 v[4:5], v[4:5], v[26:27], v[8:9] op_sel_hi:[1,0,1]
	v_cvt_pk_bf16_f32 v2, v2, v3
	s_nop 0
	v_cvt_pk_bf16_f32 v3, v4, v5
	global_store_dwordx2 v[28:29], v[2:3], off offset:96
	s_waitcnt lgkmcnt(0)
